# ride-along conv_w: second tile of a call loaded in the prologue behind the first (selects moved to prologue end, fresh regs, counted wait)
# baseline (speedup 1.0000x reference)
;     ...
;     const int nkt = K / 64, ntiles = (Ntot / 128) * nkt;
;     float v[16];
;     ...
;     const int cstride = nwg ? nwg : (int)gridDim.x; bid -= wg0;
;     if (bid < 0) return;
;     if (bid < ntiles) CONVW_LOAD(bid);
.LBB0_839:
	s_add_i32 s30, s2, -3
	s_cmp_lt_u32 s30, 3
	s_cselect_b64 s[30:31], -1, 0
	s_and_b64 s[30:31], s[6:7], s[30:31]
	s_and_b64 vcc, exec, s[30:31]
	s_cbranch_vccnz .LBB0_802
	s_nop 0
	v_mov_b32_e32 v11, v192
	s_mov_b32 s70, s52
	s_lshr_b32 s30, s55, 6
	s_mul_i32 s31, s30, s57
	s_cmp_gt_i32 s70, -1
	s_cselect_b64 s[68:69], -1, 0
	s_cmp_lt_i32 s70, s31
	s_cselect_b64 s[72:73], -1, 0
	s_and_b64 s[68:69], s[68:69], s[72:73]
	s_andn2_b64 vcc, exec, s[68:69]
	s_cbranch_vccnz .LBB0_802
	v_cvt_f32_u32_e32 v0, s30
	s_and_b32 s57, s70, 0xffff
	v_cvt_f32_u32_e32 v1, s57
	v_and_b32_e32 v20, 0x7f, v11
	v_rcp_iflag_f32_e32 v36, v0
	v_ashrrev_i32_e32 v62, 7, v11
	v_add_u32_e32 v23, 0x200, v11
	v_ashrrev_i32_e32 v61, 7, v23
	v_mul_f32_e32 v2, v1, v36
	v_trunc_f32_e32 v2, v2
	v_cvt_u32_f32_e32 v3, v2
	v_fma_f32 v1, -v2, v0, v1
	v_cmp_ge_f32_e64 s[68:69], |v1|, v0
	s_cmp_lg_u64 s[68:69], 0
	v_readfirstlane_b32 s57, v3
	s_addc_u32 s59, s57, 0
	s_and_b32 s68, s59, 0xffff
	s_add_i32 s57, s54, -1
	s_mul_i32 s59, s59, s30
	v_lshl_or_b32 v10, s68, 7, v20
	s_sub_i32 s59, s70, s59
	v_min_u32_e32 v0, s57, v10
	s_lshl_b32 s59, s59, 6
	v_lshlrev_b32_e32 v32, 2, v0
	s_and_b32 s59, s59, 0xffc0
	v_lshl_add_u64 v[0:1], s[4:5], 0, v[32:33]
	s_lshl_b64 s[26:27], s[26:27], 2
	v_lshl_add_u64 v[8:9], v[0:1], 0, s[26:27]
	v_add_u32_e32 v0, s59, v62
	v_add_u32_e32 v25, 0x400, v11
	v_mul_lo_u32 v32, v0, s56
	v_add_u32_e32 v2, s59, v61
	v_ashrrev_i32_e32 v60, 7, v25
	v_add_u32_e32 v27, 0x600, v11
	v_lshl_add_u64 v[0:1], v[32:33], 2, v[8:9]
	v_mul_lo_u32 v32, v2, s56
	v_add_u32_e32 v4, s59, v60
	v_ashrrev_i32_e32 v59, 7, v27
	v_add_u32_e32 v29, 0x800, v11
	v_lshl_add_u64 v[2:3], v[32:33], 2, v[8:9]
	v_mul_lo_u32 v32, v4, s56
	v_add_u32_e32 v6, s59, v59
	v_ashrrev_i32_e32 v58, 7, v29
	v_add_u32_e32 v31, 0xa00, v11
	v_lshl_add_u64 v[4:5], v[32:33], 2, v[8:9]
	v_mul_lo_u32 v32, v6, s56
	v_add_u32_e32 v12, s59, v58
	v_ashrrev_i32_e32 v57, 7, v31
	v_add_u32_e32 v35, 0xc00, v11
	v_lshl_add_u64 v[6:7], v[32:33], 2, v[8:9]
	v_mul_lo_u32 v32, v12, s56
	v_add_u32_e32 v14, s59, v57
	v_ashrrev_i32_e32 v56, 7, v35
	v_add_u32_e32 v37, 0xe00, v11
	v_lshl_add_u64 v[12:13], v[32:33], 2, v[8:9]
	v_mul_lo_u32 v32, v14, s56
	v_add_u32_e32 v16, s59, v56
	v_ashrrev_i32_e32 v55, 7, v37
	v_lshl_add_u64 v[14:15], v[32:33], 2, v[8:9]
	v_mul_lo_u32 v32, v16, s56
	v_add_u32_e32 v18, s59, v55
	v_lshl_add_u64 v[16:17], v[32:33], 2, v[8:9]
	v_mul_lo_u32 v32, v18, s56
	v_lshl_add_u64 v[18:19], v[32:33], 2, v[8:9]
	global_load_dword v139, v[0:1], off
	global_load_dword v140, v[2:3], off
	global_load_dword v141, v[4:5], off
	s_nop 0
	global_load_dword v142, v[6:7], off
	s_nop 0
	global_load_dword v143, v[12:13], off
	global_load_dword v144, v[14:15], off
	s_nop 0
	global_load_dword v145, v[16:17], off
	s_nop 0
	global_load_dword v146, v[18:19], off
	v_add_u32_e32 v0, 0x1000, v11
	v_ashrrev_i32_e32 v54, 7, v0
	v_add_u32_e32 v2, 0x1200, v11
	v_add_u32_e32 v0, s59, v54
	v_ashrrev_i32_e32 v53, 7, v2
	v_add_u32_e32 v4, 0x1400, v11
	v_mul_lo_u32 v32, v0, s56
	v_add_u32_e32 v2, s59, v53
	v_ashrrev_i32_e32 v52, 7, v4
	v_lshl_add_u64 v[0:1], v[32:33], 2, v[8:9]
	v_mul_lo_u32 v32, v2, s56
	v_add_u32_e32 v4, s59, v52
	v_lshl_add_u64 v[2:3], v[32:33], 2, v[8:9]
	v_mul_lo_u32 v32, v4, s56
	v_lshl_add_u64 v[4:5], v[32:33], 2, v[8:9]
	global_load_dword v147, v[0:1], off
	global_load_dword v148, v[2:3], off
	global_load_dword v149, v[4:5], off
	v_add_u32_e32 v0, 0x1600, v11
	v_add_u32_e32 v1, 0x1800, v11
	v_ashrrev_i32_e32 v51, 7, v0
	v_add_u32_e32 v2, 0x1a00, v11
	v_ashrrev_i32_e32 v50, 7, v1
	v_add_u32_e32 v0, s59, v51
	v_ashrrev_i32_e32 v49, 7, v2
	v_add_u32_e32 v1, s59, v50
	v_mul_lo_u32 v32, v0, s56
	v_lshl_add_u64 v[12:13], v[32:33], 2, v[8:9]
	v_mul_lo_u32 v32, v1, s56
	v_cmp_gt_u32_e32 vcc, s54, v10
	v_add_u32_e32 v10, s59, v49
	v_lshl_add_u64 v[14:15], v[32:33], 2, v[8:9]
	v_mul_lo_u32 v32, v10, s56
	v_add_u32_e32 v10, 0x1c00, v11
	v_ashrrev_i32_e32 v48, 7, v10
	v_add_u32_e32 v10, s59, v48
	v_mul_f32_e32 v36, 0x4f7ffffe, v36
	v_cvt_u32_f32_e32 v45, v36
	s_add_u32 s26, s4, s26
	s_addc_u32 s27, s5, s27
	v_ashrrev_i32_e32 v23, 5, v23
	v_ashrrev_i32_e32 v25, 5, v25
	v_ashrrev_i32_e32 v27, 5, v27
	v_ashrrev_i32_e32 v29, 5, v29
	v_ashrrev_i32_e32 v31, 5, v31
	v_ashrrev_i32_e32 v35, 5, v35
	v_ashrrev_i32_e32 v37, 5, v37
	v_mul_lo_u32 v65, v60, s82
	v_mul_lo_u32 v66, v59, s82
	v_mul_lo_u32 v67, v58, s82
	v_mul_lo_u32 v68, v57, s82
	v_mul_lo_u32 v69, v56, s82
	v_mul_lo_u32 v70, v55, s82
	v_mul_lo_u32 v71, v54, s82
	v_mul_lo_u32 v72, v53, s82
	v_mul_lo_u32 v73, v52, s82
	v_mul_lo_u32 v74, v51, s82
	v_mul_lo_u32 v75, v50, s82
	v_mul_lo_u32 v76, v49, s82
	v_mul_lo_u32 v77, v48, s82
	v_and_b32_e32 v40, 0x7f, v23
	v_and_b32_e32 v41, 0x7f, v25
	v_and_b32_e32 v42, 0x7f, v27
	v_and_b32_e32 v43, 0x7f, v29
	v_and_b32_e32 v44, 0x7f, v31
	v_and_b32_e32 v46, 0x7f, v35
	v_and_b32_e32 v63, 0x7f, v37
	v_lshl_add_u64 v[128:129], v[32:33], 2, v[8:9]
	v_mul_lo_u32 v32, v10, s56
	v_add_u32_e32 v10, 0x1e00, v11
	v_ashrrev_i32_e32 v47, 7, v10
	v_add_u32_e32 v10, s59, v47
	v_lshl_add_u64 v[130:131], v[32:33], 2, v[8:9]
	v_mul_lo_u32 v32, v10, s56
	v_lshl_add_u64 v[132:133], v[32:33], 2, v[8:9]
; #define LDS_BARRIER() do { asm volatile("s_waitcnt lgkmcnt(0)" ::: "memory"); __builtin_amdgcn_s_barrier(); asm volatile("" ::: "memory"); } while (0)
;     ...
;     const int cstride = nwg ? nwg : (int)gridDim.x; bid -= wg0;
;     if (bid < 0) return;
;     if (bid < ntiles) CONVW_LOAD(bid);
;     for (int t = bid; t < ntiles; t += cstride) {
;         const int n0 = (t / nkt) * 128, k0 = (t % nkt) * 64;
; #pragma unroll
;         for (int it = 0; it < 16; ++it) { const int e = tid + 512 * it, kk = e >> 7, nn = e & 127; tile[kk * 129 + nn] = v[it]; }
;         LDS_BARRIER();
;         if (t + cstride < ntiles) CONVW_LOAD(t + cstride);
	global_load_dword v134, v[12:13], off
	global_load_dword v135, v[14:15], off
	global_load_dword v136, v[128:129], off
	global_load_dword v137, v[130:131], off
	global_load_dword v138, v[132:133], off
	v_ashrrev_i32_e32 v21, 5, v11
	v_and_b32_e32 v39, 0x7f, v21
	v_lshlrev_b32_e32 v16, 1, v11
	s_lshl_b32 s59, s58, 7
	v_and_b32_e32 v16, 62, v16
	s_cmp_lt_i32 s58, 0
	v_lshlrev_b32_e32 v32, 1, v16
	s_cselect_b64 s[4:5], -1, 0
	v_mad_u32_u24 v38, v16, s82, 0
	v_lshl_add_u64 v[16:17], s[28:29], 0, v[32:33]
	v_readfirstlane_b32 s28, v45
	s_sub_i32 s29, 0, s30
	s_mul_i32 s29, s29, s28
	s_mul_hi_u32 s29, s28, s29
	v_lshl_add_u32 v19, v20, 2, 0
	v_mul_lo_u32 v11, v62, s82
	v_mul_lo_u32 v32, v61, s82
	v_mul_lo_u32 v78, v47, s82
	s_add_i32 s58, s28, s29
	s_lshl_b32 s28, s30, 6
	s_lshl_b32 s69, s34, 6
	v_lshl_add_u32 v22, v21, 2, v38
	v_lshl_add_u32 v24, v23, 2, v38
	v_lshl_add_u32 v26, v25, 2, v38
	v_lshl_add_u32 v28, v27, 2, v38
	v_lshl_add_u32 v30, v29, 2, v38
	v_lshl_add_u32 v34, v31, 2, v38
	v_lshl_add_u32 v36, v35, 2, v38
	v_lshl_add_u32 v38, v37, 2, v38
	v_or_b32_e32 v39, s59, v39
	v_or_b32_e32 v40, s59, v40
	v_or_b32_e32 v41, s59, v41
	v_or_b32_e32 v42, s59, v42
	v_or_b32_e32 v43, s59, v43
	v_or_b32_e32 v44, s59, v44
	v_or_b32_e32 v45, s59, v46
	v_or_b32_e32 v46, s59, v63
	s_sub_i32 s59, 0, s28
	s_lshl_b32 s68, s70, 6
	v_add_u32_e32 v47, s69, v47
	v_add_u32_e32 v48, s69, v48
	v_add_u32_e32 v49, s69, v49
	v_add_u32_e32 v50, s69, v50
	v_add_u32_e32 v51, s69, v51
	v_add_u32_e32 v52, s69, v52
	v_add_u32_e32 v53, s69, v53
	v_add_u32_e32 v54, s69, v54
	v_add_u32_e32 v55, s69, v55
	v_add_u32_e32 v56, s69, v56
	v_add_u32_e32 v57, s69, v57
	v_add_u32_e32 v58, s69, v58
	v_add_u32_e32 v59, s69, v59
	v_add_u32_e32 v60, s69, v60
	v_add_u32_e32 v61, s69, v61
	v_add_u32_e32 v62, s69, v62
	v_add_u32_e32 v63, v19, v11
	v_add_u32_e32 v64, v19, v32
	v_add_u32_e32 v65, v19, v65
	v_add_u32_e32 v66, v19, v66
	v_add_u32_e32 v67, v19, v67
	v_add_u32_e32 v68, v19, v68
	v_add_u32_e32 v69, v19, v69
	v_add_u32_e32 v70, v19, v70
	v_add_u32_e32 v71, v19, v71
	v_add_u32_e32 v72, v19, v72
	v_add_u32_e32 v73, v19, v73
	v_add_u32_e32 v74, v19, v74
	v_add_u32_e32 v75, v19, v75
	v_add_u32_e32 v76, v19, v76
	v_add_u32_e32 v77, v19, v77
	v_add_u32_e32 v78, v19, v78
	s_add_i32 s71, s70, s34
	s_cmp_ge_i32 s71, s31
	s_cbranch_scc1 .Lcv_no2
	s_abs_i32 s73, s71
	s_mul_hi_u32 s75, s73, s58
	s_mul_i32 s76, s75, s30
	s_sub_i32 s73, s73, s76
	s_ashr_i32 s72, s71, 31
	s_add_i32 s76, s75, 1
	s_sub_i32 s77, s73, s30
	s_cmp_ge_u32 s73, s30
	s_cselect_b32 s75, s76, s75
	s_cselect_b32 s73, s77, s73
	s_add_i32 s76, s75, 1
	s_cmp_ge_u32 s73, s30
	s_cselect_b32 s73, s76, s75
	s_xor_b32 s73, s73, s72
	s_sub_i32 s72, s73, s72
	v_lshl_or_b32 v0, s72, 7, v20
	v_cmp_gt_i32_e64 s[98:99], s54, v0
	v_min_i32_e32 v0, s57, v0
	s_mul_i32 s72, s59, s72
	v_ashrrev_i32_e32 v1, 31, v0
	s_add_i32 s72, s72, s68
	v_lshl_add_u64 v[18:19], v[0:1], 2, s[26:27]
	v_add_u32_e32 v0, s72, v62
	v_mul_lo_u32 v32, v0, s56
	v_lshl_add_u64 v[0:1], v[32:33], 2, v[18:19]
	global_load_dword v156, v[0:1], off
	v_add_u32_e32 v1, s72, v61
	v_mul_lo_u32 v32, v1, s56
	v_lshl_add_u64 v[2:3], v[32:33], 2, v[18:19]
	global_load_dword v157, v[2:3], off
	v_add_u32_e32 v2, s72, v60
	v_mul_lo_u32 v32, v2, s56
	v_lshl_add_u64 v[2:3], v[32:33], 2, v[18:19]
	global_load_dword v158, v[2:3], off
	v_add_u32_e32 v3, s72, v59
	v_mul_lo_u32 v32, v3, s56
	v_lshl_add_u64 v[4:5], v[32:33], 2, v[18:19]
	global_load_dword v159, v[4:5], off
	v_add_u32_e32 v4, s72, v58
	v_mul_lo_u32 v32, v4, s56
	v_lshl_add_u64 v[4:5], v[32:33], 2, v[18:19]
	global_load_dword v160, v[4:5], off
	v_add_u32_e32 v5, s72, v57
	v_mul_lo_u32 v32, v5, s56
	v_lshl_add_u64 v[6:7], v[32:33], 2, v[18:19]
	global_load_dword v161, v[6:7], off
	v_add_u32_e32 v6, s72, v56
	v_mul_lo_u32 v32, v6, s56
	v_lshl_add_u64 v[6:7], v[32:33], 2, v[18:19]
	global_load_dword v162, v[6:7], off
	v_add_u32_e32 v7, s72, v55
	v_mul_lo_u32 v32, v7, s56
	v_lshl_add_u64 v[8:9], v[32:33], 2, v[18:19]
	global_load_dword v163, v[8:9], off
	v_add_u32_e32 v8, s72, v54
	v_mul_lo_u32 v32, v8, s56
	v_lshl_add_u64 v[8:9], v[32:33], 2, v[18:19]
	global_load_dword v164, v[8:9], off
	v_add_u32_e32 v9, s72, v53
	v_mul_lo_u32 v32, v9, s56
	v_lshl_add_u64 v[10:11], v[32:33], 2, v[18:19]
	global_load_dword v165, v[10:11], off
	v_add_u32_e32 v10, s72, v52
	v_mul_lo_u32 v32, v10, s56
	v_lshl_add_u64 v[10:11], v[32:33], 2, v[18:19]
	global_load_dword v166, v[10:11], off
	v_add_u32_e32 v11, s72, v51
	v_mul_lo_u32 v32, v11, s56
	v_lshl_add_u64 v[12:13], v[32:33], 2, v[18:19]
	global_load_dword v167, v[12:13], off
	v_add_u32_e32 v12, s72, v50
	v_mul_lo_u32 v32, v12, s56
	v_lshl_add_u64 v[12:13], v[32:33], 2, v[18:19]
	global_load_dword v168, v[12:13], off
	v_add_u32_e32 v13, s72, v49
	v_mul_lo_u32 v32, v13, s56
	v_lshl_add_u64 v[14:15], v[32:33], 2, v[18:19]
	global_load_dword v169, v[14:15], off
	v_add_u32_e32 v14, s72, v48
	v_mul_lo_u32 v32, v14, s56
	v_lshl_add_u64 v[14:15], v[32:33], 2, v[18:19]
	global_load_dword v170, v[14:15], off
	v_add_u32_e32 v15, s72, v47
	v_mul_lo_u32 v32, v15, s56
	v_lshl_add_u64 v[18:19], v[32:33], 2, v[18:19]
	global_load_dword v171, v[18:19], off
	s_waitcnt vmcnt(16)
	s_branch .Lcv_join

;     ...
;     const int cstride = nwg ? nwg : (int)gridDim.x; bid -= wg0;
;     if (bid < 0) return;
;     if (bid < ntiles) CONVW_LOAD(bid);
;     for (int t = bid; t < ntiles; t += cstride) {
;         const int n0 = (t / nkt) * 128, k0 = (t % nkt) * 64;
; #pragma unroll
;         for (int it = 0; it < 16; ++it) { const int e = tid + 512 * it, kk = e >> 7, nn = e & 127; tile[kk * 129 + nn] = v[it]; }
.Lcv_join:
	v_cndmask_b32_e32 v0, 0, v139, vcc
	v_cndmask_b32_e32 v1, 0, v140, vcc
	v_cndmask_b32_e32 v2, 0, v141, vcc
	v_cndmask_b32_e32 v3, 0, v142, vcc
	v_cndmask_b32_e32 v4, 0, v143, vcc
	v_cndmask_b32_e32 v5, 0, v144, vcc
	v_cndmask_b32_e32 v6, 0, v145, vcc
	v_cndmask_b32_e32 v7, 0, v146, vcc
	v_cndmask_b32_e32 v8, 0, v147, vcc
	v_cndmask_b32_e32 v9, 0, v148, vcc
	v_cndmask_b32_e32 v10, 0, v149, vcc
	v_cndmask_b32_e32 v11, 0, v134, vcc
	v_cndmask_b32_e32 v12, 0, v135, vcc
	v_cndmask_b32_e32 v13, 0, v136, vcc
	v_cndmask_b32_e32 v14, 0, v137, vcc
	v_cndmask_b32_e32 v15, 0, v138, vcc
	s_branch .LBB0_843

; #define LDS_BARRIER() do { asm volatile("s_waitcnt lgkmcnt(0)" ::: "memory"); __builtin_amdgcn_s_barrier(); asm volatile("" ::: "memory"); } while (0)
;     ...
;     for (int t = bid; t < ntiles; t += cstride) {
;         const int n0 = (t / nkt) * 128, k0 = (t % nkt) * 64;
; #pragma unroll
;         for (int it = 0; it < 16; ++it) { const int e = tid + 512 * it, kk = e >> 7, nn = e & 127; tile[kk * 129 + nn] = v[it]; }
;         LDS_BARRIER();
;         if (t + cstride < ntiles) CONVW_LOAD(t + cstride);
; #pragma unroll
;         for (int it = 0; it < 8; ++it) {
;             const int e = tid + 512 * it, nn = e >> 5, kp = e & 31, n = n0 + nn;
;             const int dr = (inter >= 0) ? ((n >> 7) * 256 + inter * 128 + (n & 127)) : n;
;             h16x2 o; o[0] = (h16)tile[(2 * kp) * 129 + nn]; o[1] = (h16)tile[(2 * kp + 1) * 129 + nn];
;             gst((h16x2*)(dst + (unsigned)dr * K + k0 + 2 * kp), o);
.LBB0_843:
	ds_write_b32 v63, v0
	ds_write_b32 v64, v1
	ds_write_b32 v65, v2
	ds_write_b32 v66, v3
	ds_write_b32 v67, v4
	ds_write_b32 v68, v5
	ds_write_b32 v69, v6
	ds_write_b32 v70, v7
	ds_write_b32 v71, v8
	ds_write_b32 v72, v9
	ds_write_b32 v73, v10
	ds_write_b32 v74, v11
	ds_write_b32 v75, v12
	ds_write_b32 v76, v13
	ds_write_b32 v77, v14
	ds_write_b32 v78, v15
	s_add_i32 s71, s70, s34
	s_waitcnt lgkmcnt(0)
	s_barrier
	s_cmp_ge_i32 s71, s31
	s_cselect_b64 s[28:29], -1, 0
	s_and_b64 vcc, exec, s[28:29]
	s_cbranch_vccnz .LBB0_842
	s_waitcnt vmcnt(0)
	v_cndmask_b32_e64 v0, 0, v156, s[98:99]
	v_cndmask_b32_e64 v1, 0, v157, s[98:99]
	v_cndmask_b32_e64 v2, 0, v158, s[98:99]
	v_cndmask_b32_e64 v3, 0, v159, s[98:99]
	v_cndmask_b32_e64 v4, 0, v160, s[98:99]
	v_cndmask_b32_e64 v5, 0, v161, s[98:99]
	v_cndmask_b32_e64 v6, 0, v162, s[98:99]
	v_cndmask_b32_e64 v7, 0, v163, s[98:99]
	v_cndmask_b32_e64 v8, 0, v164, s[98:99]
	v_cndmask_b32_e64 v9, 0, v165, s[98:99]
	v_cndmask_b32_e64 v10, 0, v166, s[98:99]
	v_cndmask_b32_e64 v11, 0, v167, s[98:99]
	v_cndmask_b32_e64 v12, 0, v168, s[98:99]
	v_cndmask_b32_e64 v13, 0, v169, s[98:99]
	v_cndmask_b32_e64 v14, 0, v170, s[98:99]
	v_cndmask_b32_e64 v15, 0, v171, s[98:99]
	s_branch .LBB0_842
